# P2 diff loop: ring-slot registers and tile counter advance inside the step (4 SALU instead of 9 at the step boundary), loop control laid out for one taken branch per step instead of three
# speedup vs baseline: 1.0010x; 1.0010x over previous
; #define LAS __attribute__((address_space(3)))
; #define ATT_KREAD(dst, c) do { _Pragma("unroll") for (int kb = 0; kb < 4; ++kb) _Pragma("unroll") for (int ds = 0; ds < 2; ++ds) \
;                 dst[kb * 2 + ds] = *(const LAS bf16x8*)(bp + (c) * 8192 + kb * 2048 + kfo + (((unsigned)(4 * ds + quad) ^ ksw) * 16)); } while (0)
; #define ATT_SMMA(sv, kf, c) do { _Pragma("unroll") for (int kb = 0; kb < 4; ++kb) { sv[kb] = (f32x4){sinit, sinit, sinit, sinit}; _Pragma("unroll") for (int ds = 0; ds < 2; ++ds) \
;                 sv[kb] = __builtin_amdgcn_mfma_f32_16x16x32_bf16(kf[kb * 2 + ds], qf[c][ds], sv[kb], 0, 0, 0); } } while (0)
; #define ATT_PV(c, lo_, hi_, eb0) do { _Pragma("unroll") for (int e = 0; e < 4; ++e) _Pragma("unroll") for (int ks = 0; ks < 2; ++ks) \
;                 O[c][(eb0) + e] = __builtin_amdgcn_mfma_f32_16x16x32_bf16(__builtin_shufflevector(lo_[e * 2 + ks], hi_[e * 2 + ks], 0, 1, 2, 3, 4, 5, 6, 7), P[c][ks], O[c][(eb0) + e], 0, 0, 0); } while (0)
; #define ATT_SB __builtin_amdgcn_sched_barrier(0)
; template <bool DIFF>
; __device__ __forceinline__ void attn_item(LAS unsigned char* lds, const bf16_t* Z, bf16_t* MIX, int b, int h, int t, float lam, float shift, const float* gain, int tid, int wid, int lane) {
;     ...
;     for (int kt = 0; kt < nkt; ++kt) {
;         const int bnx = (bcur == 2) ? 0 : bcur + 1, bn2 = (bnx == 2) ? 0 : bnx + 1;
;         const bool more2 = (kt + 2 < nkt);
;         if (more2) ATT_DMA(kt + 2, bn2);
;         if (kt <= cq) {
;             LAS unsigned char* bp = lds + bcur * ATT_RING;
;             const float msk = 0.f;
;             const float sinit = DIFF ? (msk - shift) : 0.f;
;             bf16x8 kfA[8], kfB[8]; s16x4 vAl[8], vAh[8], vBl[8], vBh[8];
;             f32x4 s0[4], s1[4];
;             bf16x8 P[NC][2];
;             const unsigned bpa = (unsigned)(size_t)bp;
;     ...
;             ATT_KREAD(kfA, 0); ATT_SB;
;             if (DIFF) { ATT_KREAD(kfB, NC - 1); ATT_SMMA(s0, kfA, 0); ATT_SB;
;                         ATT_VISSUE(vAl, vAh, 0); ATT_SMMA(s1, kfB, NC - 1); ATT_SOFT(s0, 0); ATT_SB;
;                         ATT_SOFT(s1, NC - 1); ATT_PVW(0, vAl, vAh, 0); ATT_SB;
;                         ATT_VISSUE(vBl, vBh, 4); ATT_PV(NC - 1, vAl, vAh, 0); ATT_SB;
;                         ATT_PVW(0, vBl, vBh, 4); ATT_PV(NC - 1, vBl, vBh, 4); ATT_SB; }
.Ldx_b0:
	s_barrier
	s_mov_b32 s15, 1
	s_and_b32 s0, s15, 3
	s_lshl_b32 s0, s0, 15
	s_add_i32 s1, s15, 3
	s_and_b32 s1, s1, 3
	s_lshl_b32 s1, s1, 15
	s_add_i32 s16, s15, 2
	s_and_b32 s16, s16, 3
	s_lshl_b32 s16, s16, 15
	s_add_i32 s16, s16, s90
	s_add_i32 s2, s70, 2
	s_cmp_gt_u32 s15, s83
	s_cbranch_scc1 .Ldx_pvo
.Ldx_loop:
	s_waitcnt lgkmcnt(0)
	v_add_u32_e32 v119, s0, v144
	v_add_u32_e32 v116, v119, v145
	v_add_u32_e32 v117, v119, v146
	ds_read_b128 v[84:87], v116
	ds_read_b128 v[88:91], v116 offset:2048
	ds_read_b128 v[92:95], v117
	ds_read_b128 v[96:99], v117 offset:2048
	ds_read_b128 v[100:103], v116 offset:4096
	ds_read_b128 v[104:107], v116 offset:6144
	ds_read_b128 v[108:111], v117 offset:4096
	ds_read_b128 v[112:115], v117 offset:6144
	v_add_u32_e32 v118, s1, v143
	v_add_u32_e32 v120, v118, v138
	v_add_u32_e32 v121, v118, v137
	v_add_u32_e32 v122, v118, v136
	v_add_u32_e32 v123, v118, v129
	v_mfma_f32_16x16x32_bf16 v[64:67], v[148:151], v[220:223], v[64:67]
	v_add_f32_e32 v131, v131, v188
	v_add_f32_e32 v131, v131, v189
	v_mfma_f32_16x16x32_bf16 v[60:63], v[156:159], v[220:223], v[60:63]
	v_add_f32_e32 v131, v131, v190
	v_add_f32_e32 v131, v131, v191
	v_mfma_f32_16x16x32_bf16 v[56:59], v[148:151], v[228:231], v[56:59]
	v_add_f32_e32 v131, v131, v192
	v_add_f32_e32 v131, v131, v193
	v_mfma_f32_16x16x32_bf16 v[52:55], v[156:159], v[228:231], v[52:55]
	v_add_f32_e32 v131, v131, v194
	v_add_f32_e32 v131, v131, v195
	v_mfma_f32_16x16x32_bf16 v[64:67], v[152:155], v[224:227], v[64:67]
	v_add_f32_e32 v131, v131, v196
	v_add_f32_e32 v131, v131, v197
	v_mfma_f32_16x16x32_bf16 v[60:63], v[160:163], v[224:227], v[60:63]
	v_add_f32_e32 v131, v131, v198
	v_add_f32_e32 v131, v131, v199
	v_mfma_f32_16x16x32_bf16 v[56:59], v[152:155], v[232:235], v[56:59]
	v_add_f32_e32 v131, v131, v200
	v_add_f32_e32 v131, v131, v201
	v_mfma_f32_16x16x32_bf16 v[52:55], v[160:163], v[232:235], v[52:55]
	v_add_f32_e32 v131, v131, v202
	v_add_f32_e32 v131, v131, v203
	ds_read_b64_tr_b16 v[148:149], v120
	ds_read_b64_tr_b16 v[150:151], v120 offset:4096
	ds_read_b64_tr_b16 v[152:153], v120 offset:8192
	ds_read_b64_tr_b16 v[154:155], v120 offset:12288
	ds_read_b64_tr_b16 v[156:157], v121
	ds_read_b64_tr_b16 v[158:159], v121 offset:4096
	ds_read_b64_tr_b16 v[160:161], v121 offset:8192
	ds_read_b64_tr_b16 v[162:163], v121 offset:12288
	v_mfma_f32_16x16x32_bf16 v[48:51], v[164:167], v[220:223], v[48:51]
	v_add_f32_e32 v130, v130, v204
	v_add_f32_e32 v130, v130, v205
	v_mfma_f32_16x16x32_bf16 v[40:43], v[172:175], v[220:223], v[40:43]
	v_add_f32_e32 v130, v130, v206
	v_add_f32_e32 v130, v130, v207
	v_mfma_f32_16x16x32_bf16 v[44:47], v[164:167], v[228:231], v[44:47]
	v_add_f32_e32 v130, v130, v208
	v_add_f32_e32 v130, v130, v209
	v_mfma_f32_16x16x32_bf16 v[36:39], v[172:175], v[228:231], v[36:39]
	v_add_f32_e32 v130, v130, v210
	v_add_f32_e32 v130, v130, v211
	v_mfma_f32_16x16x32_bf16 v[48:51], v[168:171], v[224:227], v[48:51]
	v_add_f32_e32 v130, v130, v212
	v_add_f32_e32 v130, v130, v213
	v_mfma_f32_16x16x32_bf16 v[40:43], v[176:179], v[224:227], v[40:43]
	v_add_f32_e32 v130, v130, v214
	v_add_f32_e32 v130, v130, v215
	v_mfma_f32_16x16x32_bf16 v[44:47], v[168:171], v[232:235], v[44:47]
	v_add_f32_e32 v130, v130, v216
	v_add_f32_e32 v130, v130, v217
	v_mfma_f32_16x16x32_bf16 v[36:39], v[176:179], v[232:235], v[36:39]
	v_add_f32_e32 v130, v130, v218
	v_add_f32_e32 v130, v130, v219
	ds_read_b64_tr_b16 v[164:165], v122
	ds_read_b64_tr_b16 v[166:167], v122 offset:4096
	ds_read_b64_tr_b16 v[168:169], v122 offset:8192
	ds_read_b64_tr_b16 v[170:171], v122 offset:12288
	ds_read_b64_tr_b16 v[172:173], v123
	ds_read_b64_tr_b16 v[174:175], v123 offset:4096
	ds_read_b64_tr_b16 v[176:177], v123 offset:8192
	ds_read_b64_tr_b16 v[178:179], v123 offset:12288
	s_cmp_ge_u32 s15, s70
	s_cbranch_scc1 .Ldx_nd
	s_add_u32 s18, s4, 0xfffff800
	s_addc_u32 s19, s5, -1
	s_mov_b32 m0, s16
	s_add_u32 s22, s18, 0x80
	s_addc_u32 s23, s19, 0
	global_load_lds_dwordx4 v180, s[18:19]
	s_add_i32 m0, s16, 0x2000
	s_add_u32 s24, s4, 0x70000
	s_addc_u32 s25, s5, 0
	global_load_lds_dwordx4 v180, s[22:23]
	s_add_i32 m0, s16, 0x4000
	s_nop 0
	global_load_lds_dwordx4 v132, s[4:5]
	s_add_i32 m0, s16, 0x6000
	s_add_u32 s4, s4, 0xe0000
	s_addc_u32 s5, s5, 0
	global_load_lds_dwordx4 v132, s[24:25]
; #define ATT_KREAD(dst, c) do { _Pragma("unroll") for (int kb = 0; kb < 4; ++kb) _Pragma("unroll") for (int ds = 0; ds < 2; ++ds) \
;                 dst[kb * 2 + ds] = *(const LAS bf16x8*)(bp + (c) * 8192 + kb * 2048 + kfo + (((unsigned)(4 * ds + quad) ^ ksw) * 16)); } while (0)
; #define ATT_SMMA(sv, kf, c) do { _Pragma("unroll") for (int kb = 0; kb < 4; ++kb) { sv[kb] = (f32x4){sinit, sinit, sinit, sinit}; _Pragma("unroll") for (int ds = 0; ds < 2; ++ds) \
;                 sv[kb] = __builtin_amdgcn_mfma_f32_16x16x32_bf16(kf[kb * 2 + ds], qf[c][ds], sv[kb], 0, 0, 0); } } while (0)
; #define ATT_PV(c, lo_, hi_, eb0) do { _Pragma("unroll") for (int e = 0; e < 4; ++e) _Pragma("unroll") for (int ks = 0; ks < 2; ++ks) \
;                 O[c][(eb0) + e] = __builtin_amdgcn_mfma_f32_16x16x32_bf16(__builtin_shufflevector(lo_[e * 2 + ks], hi_[e * 2 + ks], 0, 1, 2, 3, 4, 5, 6, 7), P[c][ks], O[c][(eb0) + e], 0, 0, 0); } while (0)
; #define ATT_PVW(c, lo_, hi_, eb0) do { ATT_W4(12, lo_, hi_, 0); ATT_PV1(c, lo_, hi_, eb0, 0); ATT_W4(8, lo_, hi_, 1); ATT_PV1(c, lo_, hi_, eb0, 1); \
;                 ATT_W4(4, lo_, hi_, 2); ATT_PV1(c, lo_, hi_, eb0, 2); ATT_W4(0, lo_, hi_, 3); ATT_PV1(c, lo_, hi_, eb0, 3); } while (0)
; #define ATT_SB __builtin_amdgcn_sched_barrier(0)
; template <bool DIFF>
; __device__ __forceinline__ void attn_item(LAS unsigned char* lds, const bf16_t* Z, bf16_t* MIX, int b, int h, int t, float lam, float shift, const float* gain, int tid, int wid, int lane) {
;     ...
;             ATT_KREAD(kfA, 0); ATT_SB;
;             if (DIFF) { ATT_KREAD(kfB, NC - 1); ATT_SMMA(s0, kfA, 0); ATT_SB;
;                         ATT_VISSUE(vAl, vAh, 0); ATT_SMMA(s1, kfB, NC - 1); ATT_SOFT(s0, 0); ATT_SB;
;                         ATT_SOFT(s1, NC - 1); ATT_PVW(0, vAl, vAh, 0); ATT_SB;
;                         ATT_VISSUE(vBl, vBh, 4); ATT_PV(NC - 1, vAl, vAh, 0); ATT_SB;
;                         ATT_PVW(0, vBl, vBh, 4); ATT_PV(NC - 1, vBl, vBh, 4); ATT_SB; }
.Ldx_nd:
	s_add_i32 s16, s1, s90
	s_mov_b32 s1, s0
	s_add_i32 s15, s15, 1
	s_waitcnt lgkmcnt(15)
	v_mfma_f32_16x16x32_bf16 v[188:191], v[84:87], v[80:83], v[0:3]
	v_mfma_f32_16x16x32_bf16 v[192:195], v[88:91], v[80:83], v[0:3]
	v_mfma_f32_16x16x32_bf16 v[196:199], v[100:103], v[80:83], v[0:3]
	v_mfma_f32_16x16x32_bf16 v[200:203], v[104:107], v[80:83], v[0:3]
	v_mfma_f32_16x16x32_bf16 v[188:191], v[92:95], v[76:79], v[188:191]
	v_mfma_f32_16x16x32_bf16 v[192:195], v[96:99], v[76:79], v[192:195]
	v_mfma_f32_16x16x32_bf16 v[196:199], v[108:111], v[76:79], v[196:199]
	v_mfma_f32_16x16x32_bf16 v[200:203], v[112:115], v[76:79], v[200:203]
	ds_read_b128 v[84:87], v116 offset:8192
	ds_read_b128 v[88:91], v116 offset:10240
	ds_read_b128 v[92:95], v117 offset:8192
	ds_read_b128 v[96:99], v117 offset:10240
	ds_read_b128 v[100:103], v116 offset:12288
	ds_read_b128 v[104:107], v116 offset:14336
	ds_read_b128 v[108:111], v117 offset:12288
	ds_read_b128 v[112:115], v117 offset:14336
	s_waitcnt lgkmcnt(15)
	v_mfma_f32_16x16x32_bf16 v[32:35], v[148:151], v[220:223], v[32:35]
	v_exp_f32_e32 v188, v188
	v_mfma_f32_16x16x32_bf16 v[24:27], v[156:159], v[220:223], v[24:27]
	v_exp_f32_e32 v189, v189
	v_mfma_f32_16x16x32_bf16 v[28:31], v[148:151], v[228:231], v[28:31]
	v_exp_f32_e32 v190, v190
	v_mfma_f32_16x16x32_bf16 v[20:23], v[156:159], v[228:231], v[20:23]
	v_exp_f32_e32 v191, v191
	v_mfma_f32_16x16x32_bf16 v[32:35], v[152:155], v[224:227], v[32:35]
	v_exp_f32_e32 v192, v192
	v_mfma_f32_16x16x32_bf16 v[24:27], v[160:163], v[224:227], v[24:27]
	v_exp_f32_e32 v193, v193
	v_mfma_f32_16x16x32_bf16 v[28:31], v[152:155], v[232:235], v[28:31]
	v_exp_f32_e32 v194, v194
	v_mfma_f32_16x16x32_bf16 v[20:23], v[160:163], v[232:235], v[20:23]
	v_exp_f32_e32 v195, v195
	s_waitcnt lgkmcnt(8)
	v_mfma_f32_16x16x32_bf16 v[16:19], v[164:167], v[220:223], v[16:19]
	v_exp_f32_e32 v196, v196
	v_mfma_f32_16x16x32_bf16 v[8:11], v[172:175], v[220:223], v[8:11]
	v_exp_f32_e32 v197, v197
	v_mfma_f32_16x16x32_bf16 v[12:15], v[164:167], v[228:231], v[12:15]
	v_exp_f32_e32 v198, v198
	v_mfma_f32_16x16x32_bf16 v[4:7], v[172:175], v[228:231], v[4:7]
	v_exp_f32_e32 v199, v199
	v_mfma_f32_16x16x32_bf16 v[16:19], v[168:171], v[224:227], v[16:19]
	v_exp_f32_e32 v200, v200
	v_mfma_f32_16x16x32_bf16 v[8:11], v[176:179], v[224:227], v[8:11]
	v_exp_f32_e32 v201, v201
	v_mfma_f32_16x16x32_bf16 v[12:15], v[168:171], v[232:235], v[12:15]
	v_exp_f32_e32 v202, v202
	v_mfma_f32_16x16x32_bf16 v[4:7], v[176:179], v[232:235], v[4:7]
	v_exp_f32_e32 v203, v203
	s_waitcnt lgkmcnt(0)
	v_mfma_f32_16x16x32_bf16 v[204:207], v[84:87], v[72:75], v[0:3]
	v_mfma_f32_16x16x32_bf16 v[208:211], v[88:91], v[72:75], v[0:3]
	v_mfma_f32_16x16x32_bf16 v[212:215], v[100:103], v[72:75], v[0:3]
	v_mfma_f32_16x16x32_bf16 v[216:219], v[104:107], v[72:75], v[0:3]
	v_mfma_f32_16x16x32_bf16 v[204:207], v[92:95], v[68:71], v[204:207]
	v_cvt_pk_bf16_f32 v220, v188, v189
	v_cvt_pk_bf16_f32 v221, v190, v191
	v_mfma_f32_16x16x32_bf16 v[208:211], v[96:99], v[68:71], v[208:211]
	v_cvt_pk_bf16_f32 v222, v192, v193
	v_cvt_pk_bf16_f32 v223, v194, v195
	v_mfma_f32_16x16x32_bf16 v[212:215], v[108:111], v[68:71], v[212:215]
	v_cvt_pk_bf16_f32 v224, v196, v197
	v_cvt_pk_bf16_f32 v225, v198, v199
	v_mfma_f32_16x16x32_bf16 v[216:219], v[112:115], v[68:71], v[216:219]
	v_cvt_pk_bf16_f32 v226, v200, v201
	v_cvt_pk_bf16_f32 v227, v202, v203
	v_add_u32_e32 v118, s0, v143
	v_add_u32_e32 v120, v118, v142
	v_add_u32_e32 v121, v118, v141
	v_add_u32_e32 v122, v118, v140
	v_add_u32_e32 v123, v118, v139
	ds_read_b64_tr_b16 v[148:149], v120
	ds_read_b64_tr_b16 v[150:151], v120 offset:4096
	ds_read_b64_tr_b16 v[152:153], v120 offset:8192
	ds_read_b64_tr_b16 v[154:155], v120 offset:12288
	ds_read_b64_tr_b16 v[156:157], v121
	ds_read_b64_tr_b16 v[158:159], v121 offset:4096
	ds_read_b64_tr_b16 v[160:161], v121 offset:8192
	ds_read_b64_tr_b16 v[162:163], v121 offset:12288
	ds_read_b64_tr_b16 v[164:165], v122
	ds_read_b64_tr_b16 v[166:167], v122 offset:4096
	ds_read_b64_tr_b16 v[168:169], v122 offset:8192
	ds_read_b64_tr_b16 v[170:171], v122 offset:12288
	ds_read_b64_tr_b16 v[172:173], v123
	ds_read_b64_tr_b16 v[174:175], v123 offset:4096
	ds_read_b64_tr_b16 v[176:177], v123 offset:8192
	ds_read_b64_tr_b16 v[178:179], v123 offset:12288
	s_add_i32 s0, s0, 0x8000
	s_and_b32 s0, s0, 0x18000
	v_exp_f32_e32 v204, v204
	v_exp_f32_e32 v205, v205
	v_exp_f32_e32 v206, v206
	v_exp_f32_e32 v207, v207
	v_exp_f32_e32 v208, v208
	v_exp_f32_e32 v209, v209
	v_exp_f32_e32 v210, v210
	v_exp_f32_e32 v211, v211
	v_exp_f32_e32 v212, v212
	v_exp_f32_e32 v213, v213
	v_exp_f32_e32 v214, v214
	v_exp_f32_e32 v215, v215
	v_exp_f32_e32 v216, v216
	v_exp_f32_e32 v217, v217
	v_exp_f32_e32 v218, v218
	v_exp_f32_e32 v219, v219
	v_cvt_pk_bf16_f32 v228, v204, v205
	v_cvt_pk_bf16_f32 v229, v206, v207
	v_cvt_pk_bf16_f32 v230, v208, v209
	v_cvt_pk_bf16_f32 v231, v210, v211
	v_cvt_pk_bf16_f32 v232, v212, v213
	v_cvt_pk_bf16_f32 v233, v214, v215
	v_cvt_pk_bf16_f32 v234, v216, v217
	v_cvt_pk_bf16_f32 v235, v218, v219
; #define ATT_WAITBAR_ALL() asm volatile("s_waitcnt vmcnt(0) lgkmcnt(0)\n\ts_barrier" ::: "memory")
; #define ATT_WAITBAR_ONE() do { if (DIFF) asm volatile("s_waitcnt vmcnt(4) lgkmcnt(0)\n\ts_barrier" ::: "memory"); else asm volatile("s_waitcnt vmcnt(3) lgkmcnt(0)\n\ts_barrier" ::: "memory"); } while (0)
; #define ATT_KREAD(dst, c) do { _Pragma("unroll") for (int kb = 0; kb < 4; ++kb) _Pragma("unroll") for (int ds = 0; ds < 2; ++ds) \
;                 dst[kb * 2 + ds] = *(const LAS bf16x8*)(bp + (c) * 8192 + kb * 2048 + kfo + (((unsigned)(4 * ds + quad) ^ ksw) * 16)); } while (0)
; #define ATT_SMMA(sv, kf, c) do { _Pragma("unroll") for (int kb = 0; kb < 4; ++kb) { sv[kb] = (f32x4){sinit, sinit, sinit, sinit}; _Pragma("unroll") for (int ds = 0; ds < 2; ++ds) \
;                 sv[kb] = __builtin_amdgcn_mfma_f32_16x16x32_bf16(kf[kb * 2 + ds], qf[c][ds], sv[kb], 0, 0, 0); } } while (0)
; #define ATT_PV(c, lo_, hi_, eb0) do { _Pragma("unroll") for (int e = 0; e < 4; ++e) _Pragma("unroll") for (int ks = 0; ks < 2; ++ks) \
;                 O[c][(eb0) + e] = __builtin_amdgcn_mfma_f32_16x16x32_bf16(__builtin_shufflevector(lo_[e * 2 + ks], hi_[e * 2 + ks], 0, 1, 2, 3, 4, 5, 6, 7), P[c][ks], O[c][(eb0) + e], 0, 0, 0); } while (0)
; #define ATT_PVW(c, lo_, hi_, eb0) do { ATT_W4(12, lo_, hi_, 0); ATT_PV1(c, lo_, hi_, eb0, 0); ATT_W4(8, lo_, hi_, 1); ATT_PV1(c, lo_, hi_, eb0, 1); \
;                 ATT_W4(4, lo_, hi_, 2); ATT_PV1(c, lo_, hi_, eb0, 2); ATT_W4(0, lo_, hi_, 3); ATT_PV1(c, lo_, hi_, eb0, 3); } while (0)
; #define ATT_SB __builtin_amdgcn_sched_barrier(0)
; template <bool DIFF>
; __device__ __forceinline__ void attn_item(LAS unsigned char* lds, const bf16_t* Z, bf16_t* MIX, int b, int h, int t, float lam, float shift, const float* gain, int tid, int wid, int lane) {
;     ...
;             ATT_KREAD(kfA, 0); ATT_SB;
;             if (DIFF) { ATT_KREAD(kfB, NC - 1); ATT_SMMA(s0, kfA, 0); ATT_SB;
;                         ATT_VISSUE(vAl, vAh, 0); ATT_SMMA(s1, kfB, NC - 1); ATT_SOFT(s0, 0); ATT_SB;
;                         ATT_SOFT(s1, NC - 1); ATT_PVW(0, vAl, vAh, 0); ATT_SB;
;                         ATT_VISSUE(vBl, vBh, 4); ATT_PV(NC - 1, vAl, vAh, 0); ATT_SB;
;                         ATT_PVW(0, vBl, vBh, 4); ATT_PV(NC - 1, vBl, vBh, 4); ATT_SB; }
;     ...
;         if (kt + 1 < nkt) { if (more2) ATT_WAITBAR_ONE(); else ATT_WAITBAR_ALL(); }
;         bcur = bnx;
.Ldx_eos:
	s_cmp_ge_u32 s15, s2
	s_cbranch_scc1 .Ldx_exit
	s_cmp_le_u32 s15, s70
	s_cbranch_scc0 .Ldx_wz
	s_waitcnt vmcnt(4)
.Ldx_bar:
	s_barrier
	s_cmp_gt_u32 s15, s83
	s_cbranch_scc0 .Ldx_loop
.Ldx_pvo:
	s_waitcnt lgkmcnt(0)
	v_add_u32_e32 v118, s1, v143
	v_add_u32_e32 v120, v118, v138
	v_add_u32_e32 v121, v118, v137
	v_add_u32_e32 v122, v118, v136
	v_add_u32_e32 v123, v118, v129
	v_mfma_f32_16x16x32_bf16 v[64:67], v[148:151], v[220:223], v[64:67]
	v_add_f32_e32 v131, v131, v188
	v_add_f32_e32 v131, v131, v189
	v_mfma_f32_16x16x32_bf16 v[60:63], v[156:159], v[220:223], v[60:63]
	v_add_f32_e32 v131, v131, v190
	v_add_f32_e32 v131, v131, v191
	v_mfma_f32_16x16x32_bf16 v[56:59], v[148:151], v[228:231], v[56:59]
	v_add_f32_e32 v131, v131, v192
	v_add_f32_e32 v131, v131, v193
	v_mfma_f32_16x16x32_bf16 v[52:55], v[156:159], v[228:231], v[52:55]
	v_add_f32_e32 v131, v131, v194
	v_add_f32_e32 v131, v131, v195
	v_mfma_f32_16x16x32_bf16 v[64:67], v[152:155], v[224:227], v[64:67]
	v_add_f32_e32 v131, v131, v196
	v_add_f32_e32 v131, v131, v197
	v_mfma_f32_16x16x32_bf16 v[60:63], v[160:163], v[224:227], v[60:63]
	v_add_f32_e32 v131, v131, v198
	v_add_f32_e32 v131, v131, v199
	v_mfma_f32_16x16x32_bf16 v[56:59], v[152:155], v[232:235], v[56:59]
	v_add_f32_e32 v131, v131, v200
	v_add_f32_e32 v131, v131, v201
	v_mfma_f32_16x16x32_bf16 v[52:55], v[160:163], v[232:235], v[52:55]
	v_add_f32_e32 v131, v131, v202
	v_add_f32_e32 v131, v131, v203
	ds_read_b64_tr_b16 v[148:149], v120
	ds_read_b64_tr_b16 v[150:151], v120 offset:4096
	ds_read_b64_tr_b16 v[152:153], v120 offset:8192
	ds_read_b64_tr_b16 v[154:155], v120 offset:12288
	ds_read_b64_tr_b16 v[156:157], v121
	ds_read_b64_tr_b16 v[158:159], v121 offset:4096
	ds_read_b64_tr_b16 v[160:161], v121 offset:8192
	ds_read_b64_tr_b16 v[162:163], v121 offset:12288
	v_mfma_f32_16x16x32_bf16 v[48:51], v[164:167], v[220:223], v[48:51]
	v_add_f32_e32 v130, v130, v204
	v_add_f32_e32 v130, v130, v205
	v_mfma_f32_16x16x32_bf16 v[40:43], v[172:175], v[220:223], v[40:43]
	v_add_f32_e32 v130, v130, v206
	v_add_f32_e32 v130, v130, v207
	v_mfma_f32_16x16x32_bf16 v[44:47], v[164:167], v[228:231], v[44:47]
	v_add_f32_e32 v130, v130, v208
	v_add_f32_e32 v130, v130, v209
	v_mfma_f32_16x16x32_bf16 v[36:39], v[172:175], v[228:231], v[36:39]
	v_add_f32_e32 v130, v130, v210
	v_add_f32_e32 v130, v130, v211
	v_mfma_f32_16x16x32_bf16 v[48:51], v[168:171], v[224:227], v[48:51]
	v_add_f32_e32 v130, v130, v212
	v_add_f32_e32 v130, v130, v213
	v_mfma_f32_16x16x32_bf16 v[40:43], v[176:179], v[224:227], v[40:43]
	v_add_f32_e32 v130, v130, v214
	v_add_f32_e32 v130, v130, v215
	v_mfma_f32_16x16x32_bf16 v[44:47], v[168:171], v[232:235], v[44:47]
	v_add_f32_e32 v130, v130, v216
	v_add_f32_e32 v130, v130, v217
	v_mfma_f32_16x16x32_bf16 v[36:39], v[176:179], v[232:235], v[36:39]
	v_add_f32_e32 v130, v130, v218
	v_add_f32_e32 v130, v130, v219
	ds_read_b64_tr_b16 v[164:165], v122
	ds_read_b64_tr_b16 v[166:167], v122 offset:4096
	ds_read_b64_tr_b16 v[168:169], v122 offset:8192
	ds_read_b64_tr_b16 v[170:171], v122 offset:12288
	ds_read_b64_tr_b16 v[172:173], v123
	ds_read_b64_tr_b16 v[174:175], v123 offset:4096
	ds_read_b64_tr_b16 v[176:177], v123 offset:8192
	ds_read_b64_tr_b16 v[178:179], v123 offset:12288
	s_waitcnt lgkmcnt(8)
	v_mfma_f32_16x16x32_bf16 v[32:35], v[148:151], v[220:223], v[32:35]
	v_mfma_f32_16x16x32_bf16 v[24:27], v[156:159], v[220:223], v[24:27]
	v_mfma_f32_16x16x32_bf16 v[28:31], v[148:151], v[228:231], v[28:31]
	v_mfma_f32_16x16x32_bf16 v[20:23], v[156:159], v[228:231], v[20:23]
	v_mfma_f32_16x16x32_bf16 v[32:35], v[152:155], v[224:227], v[32:35]
	v_mfma_f32_16x16x32_bf16 v[24:27], v[160:163], v[224:227], v[24:27]
	v_mfma_f32_16x16x32_bf16 v[28:31], v[152:155], v[232:235], v[28:31]
	v_mfma_f32_16x16x32_bf16 v[20:23], v[160:163], v[232:235], v[20:23]
	s_waitcnt lgkmcnt(0)
	v_mfma_f32_16x16x32_bf16 v[16:19], v[164:167], v[220:223], v[16:19]
	v_mfma_f32_16x16x32_bf16 v[8:11], v[172:175], v[220:223], v[8:11]
	v_mfma_f32_16x16x32_bf16 v[12:15], v[164:167], v[228:231], v[12:15]
	v_mfma_f32_16x16x32_bf16 v[4:7], v[172:175], v[228:231], v[4:7]
	v_mfma_f32_16x16x32_bf16 v[16:19], v[168:171], v[224:227], v[16:19]
	v_mfma_f32_16x16x32_bf16 v[8:11], v[176:179], v[224:227], v[8:11]
	v_mfma_f32_16x16x32_bf16 v[12:15], v[168:171], v[232:235], v[12:15]
	v_mfma_f32_16x16x32_bf16 v[4:7], v[176:179], v[232:235], v[4:7]
	s_add_i32 s15, s15, 1
	s_and_b32 s0, s15, 3
	s_lshl_b32 s0, s0, 15
	s_add_i32 s1, s15, 3
	s_and_b32 s1, s1, 3
	s_lshl_b32 s1, s1, 15
	s_add_i32 s16, s15, 2
	s_and_b32 s16, s16, 3
	s_lshl_b32 s16, s16, 15
	s_add_i32 s16, s16, s90
	s_branch .Ldx_eos
.Ldx_wz:
	s_waitcnt vmcnt(0)
	s_branch .Ldx_bar
